# MLA: running reference subtracted inside the QK MFMA chain (K=8 bf16 MFMA with -1/r columns), exp2 directly on MFMA output, O/l rescale only when scores exceed the reference by >8 (on top of v8)
# speedup vs baseline: 1.0417x; 1.0180x over previous
; __device__ __forceinline__ void mla_attn_phase(const Ctx&, unsigned char* ws) { const Ctx c = mk_ctx();
;     ...
;         const int ii = uu >> 8, bh = v >> 3, s8 = v & 7, qb = ii == 0 ? s8 : (ii == 1 ? 15 - s8 : (ii == 2 ? 16 + s8 : 31 - s8));
;         const int b = bh >> 4, h = bh & 15, Q0 = qb * 256, qw0 = Q0 + 32 * wid; const size_t rowbase = (size_t)b * SEQ;
;         bf16x8 qr[6];
; #pragma unroll
;         for (int s = 0; s < 6; ++s) qr[s] = *(const bf16x8*)(q + (rowbase + qw0 + r) * 1536 + h * 96 + 16 * s + 8 * hi);
;         const int ntiles = (Q0 + 256) / 64, my_last = (qw0 + 31) / 64;
;         f32x16 oa[2]; oa[0] = f32x16{}; oa[1] = f32x16{}; float mrun = -INFINITY, lrun = 0.f;
;         v4u kreg0, kreg1 = {0u, 0u, 0u, 0u}, vreg;
;     ...
;         MLA_LOAD(0);
.LBB0_744:
	s_or_b64 exec, exec, s[24:25]
	s_lshl_b32 s24, s37, 3
	s_and_b32 s24, s24, 0x7c0
	v_add_u32_e32 v2, s24, v1
	v_ashrrev_i32_e32 v3, 31, v2
	v_lshlrev_b64 v[2:3], 14, v[2:3]
	v_lshl_add_u64 v[4:5], v[122:123], 0, v[2:3]
	global_load_dwordx4 v[98:101], v[4:5], off
	s_add_i32 s24, s38, 0x100
	s_lshr_b32 s35, s24, 6
	s_lshr_b32 s24, s36, 26
	s_add_i32 s24, s24, s34
	s_add_i32 s24, s24, 31
	s_ashr_i32 s36, s24, 6
	s_lshr_b32 s24, s37, 7
	s_lshl_b32 s26, s37, 4
	s_lshl_b32 s25, s24, 24
	s_and_b32 s26, s26, 0x780
	v_mov_b32_e32 v18, v151
	v_mov_b32_e32 v19, v151
	v_lshl_add_u64 v[136:137], v[124:125], 0, v[2:3]
	s_or_b32 s96, s26, s25
	s_lshl_b32 s24, s24, 19
	s_mov_b32 s25, s97
	v_mov_b32_e32 v20, v151
	v_mov_b32_e32 v21, v151
	v_mov_b32_e32 v22, v151
	v_mov_b32_e32 v23, v151
	v_mov_b32_e32 v24, v151
	v_mov_b32_e32 v25, v151
	v_mov_b32_e32 v26, v151
	v_mov_b32_e32 v27, v151
	v_mov_b32_e32 v28, v151
	v_mov_b32_e32 v29, v151
	v_mov_b32_e32 v30, v151
	v_mov_b32_e32 v31, v151
	v_mov_b32_e32 v32, v151
	v_mov_b32_e32 v33, v151
	v_mov_b64_e32 v[2:3], v[18:19]
	v_add_u32_e32 v187, s38, v186
	v_lshl_add_u64 v[138:139], s[96:97], 0, v[126:127]
	v_lshl_add_u64 v[140:141], v[128:129], 0, s[24:25]
	v_lshl_add_u64 v[142:143], s[96:97], 0, v[130:131]
	v_lshl_add_u64 v[144:145], v[132:133], 0, s[24:25]
	s_mov_b32 s41, 0
	v_mov_b32_e32 v189, 0
	v_cmp_gt_u32_e32 vcc, 32, v206
	v_mov_b32_e32 v246, 0xbf80
	v_mov_b32_e32 v247, 0
	v_cndmask_b32_e32 v246, 0, v246, vcc
	v_mov_b32_e32 v252, 0
	v_mov_b32_e32 v253, 0
	v_mov_b32_e32 v188, 0
	s_mov_b32 s37, 63
	v_mov_b64_e32 v[4:5], v[20:21]
	v_mov_b64_e32 v[6:7], v[22:23]
	v_mov_b64_e32 v[8:9], v[24:25]
	v_mov_b64_e32 v[10:11], v[26:27]
	v_mov_b64_e32 v[12:13], v[28:29]
	v_mov_b64_e32 v[14:15], v[30:31]
	v_mov_b64_e32 v[16:17], v[32:33]

; __device__ __forceinline__ int crow(int r, int hi) { return (r & 3) + 8 * (r >> 2) + 4 * hi; }
; #define MFMA32(a, b, c) __builtin_amdgcn_mfma_f32_32x32x16_bf16((a), (b), (c), 0, 0, 0)
; __device__ __forceinline__ void mla_attn_phase(const Ctx&, unsigned char* ws) { const Ctx c = mk_ctx();
;     ...
;             if (j <= my_last) {
;                 f32x16 p0 = f32x16{}, p1 = f32x16{};
; #pragma unroll
;                 for (int s = 0; s < 6; ++s) { const bf16x8 a0 = *(const bf16x8*)(Kb + r * KLD + 16 * s + 8 * hi), a1 = *(const bf16x8*)(Kb + (r + 32) * KLD + 16 * s + 8 * hi); p0 = MFMA32(a0, qr[s], p0); p1 = MFMA32(a1, qr[s], p1); }
;                 if (64 * j + 63 > qw0) { const int qq = qw0 + r - 64 * j;
; #pragma unroll
;                     for (int i = 0; i < 16; ++i) { const int kr_ = crow(i, hi); if (kr_ > qq) p0[i] = -INFINITY; if (kr_ + 32 > qq) p1[i] = -INFINITY; } }
;                 float mx = fmaxf(p0[0], p1[0]);
; #pragma unroll
;                 for (int i = 1; i < 16; ++i) mx = fmaxf(mx, fmaxf(p0[i], p1[i]));
;                 mx = fmaxf(mx, __shfl_xor(mx, 32));
;                 const float mnew = fmaxf(mrun, mx), alpha = __builtin_amdgcn_exp2f(mrun - mnew); const bool grow = !__all(mx <= mrun); mrun = mnew; float ls = 0.f;
.LBB0_751:
	s_cmp_gt_i32 s41, s36
	s_cbranch_scc1 .LBB0_755
	v_add3_u32 v242, s43, v155, v150
	ds_read_b128 v[190:193], v242
	ds_read_b128 v[214:217], v242 offset:6656
	ds_read_b128 v[218:221], v242 offset:32
	ds_read_b128 v[222:225], v242 offset:6688
	ds_read_b128 v[226:229], v242 offset:64
	ds_read_b128 v[230:233], v242 offset:6720
	ds_read_b128 v[234:237], v242 offset:96
	ds_read_b128 v[238:241], v242 offset:6752
	s_cmp_le_i32 s37, s34
	v_mfma_f32_32x32x8_bf16 v[50:65], v[246:247], v[252:253], 0
	v_add3_u32 v243, s39, v108, v185
	v_mfma_f32_32x32x8_bf16 v[34:49], v[246:247], v[252:253], 0
	v_add_u32_e32 v243, 0x6800, v243
	s_waitcnt lgkmcnt(7)
	v_mfma_f32_32x32x16_bf16 v[50:65], v[190:193], v[66:69], v[50:65]
	v_add_u32_e32 v244, 0x1000, v243
	s_waitcnt lgkmcnt(6)
	v_mfma_f32_32x32x16_bf16 v[34:49], v[214:217], v[66:69], v[34:49]
	ds_read_b128 v[190:193], v242 offset:128
	ds_read_b128 v[214:217], v242 offset:6784
	s_waitcnt lgkmcnt(7)
	v_mfma_f32_32x32x16_bf16 v[50:65], v[218:221], v[70:73], v[50:65]
	s_waitcnt lgkmcnt(6)
	v_mfma_f32_32x32x16_bf16 v[34:49], v[222:225], v[70:73], v[34:49]
	ds_read_b128 v[218:221], v242 offset:160
	ds_read_b128 v[222:225], v242 offset:6816
	s_waitcnt lgkmcnt(7)
	v_mfma_f32_32x32x16_bf16 v[50:65], v[226:229], v[74:77], v[50:65]
	s_waitcnt lgkmcnt(6)
	v_mfma_f32_32x32x16_bf16 v[34:49], v[230:233], v[74:77], v[34:49]
	s_waitcnt lgkmcnt(5)
	v_mfma_f32_32x32x16_bf16 v[50:65], v[234:237], v[78:81], v[50:65]
	s_waitcnt lgkmcnt(4)
	v_mfma_f32_32x32x16_bf16 v[34:49], v[238:241], v[78:81], v[34:49]
	s_waitcnt lgkmcnt(3)
	v_mfma_f32_32x32x16_bf16 v[50:65], v[190:193], v[82:85], v[50:65]
	s_waitcnt lgkmcnt(2)
	v_mfma_f32_32x32x16_bf16 v[34:49], v[214:217], v[82:85], v[34:49]
	s_waitcnt lgkmcnt(1)
	v_mfma_f32_32x32x16_bf16 v[50:65], v[218:221], v[86:89], v[50:65]
	s_waitcnt lgkmcnt(0)
	v_mfma_f32_32x32x16_bf16 v[34:49], v[222:225], v[86:89], v[34:49]
	ds_read2_b64 v[226:229], v243 offset0:0 offset1:2
	ds_read2_b64 v[230:233], v243 offset0:4 offset1:6
	ds_read2_b64 v[234:237], v243 offset0:8 offset1:10
	ds_read2_b64 v[238:241], v243 offset0:12 offset1:14
	ds_read2_b64 v[190:193], v244 offset0:32 offset1:34
	ds_read2_b64 v[214:217], v244 offset0:36 offset1:38
	ds_read2_b64 v[218:221], v244 offset0:40 offset1:42
	ds_read2_b64 v[222:225], v244 offset0:44 offset1:46
	s_nop 3
	s_cbranch_scc1 .Lmla_nomask
	v_cmp_le_i32_e32 vcc, v121, v187
	s_nop 1
	v_cndmask_b32_e32 v34, v208, v34, vcc
	v_cmp_lt_i32_e32 vcc, v118, v187
	s_nop 1
	v_cndmask_b32_e32 v51, v208, v51, vcc
	v_cmp_le_i32_e32 vcc, v118, v187
	s_nop 1
	v_cndmask_b32_e32 v50, v208, v50, vcc
	v_cmp_le_i32_e32 vcc, v156, v187
	s_nop 1
	v_cndmask_b32_e32 v35, v208, v35, vcc
	v_cmp_le_i32_e32 vcc, v157, v187
	s_nop 1
	v_cndmask_b32_e32 v52, v208, v52, vcc
	v_cmp_le_i32_e32 vcc, v158, v187
	s_nop 1
	v_cndmask_b32_e32 v36, v208, v36, vcc
	v_cmp_le_i32_e32 vcc, v159, v187
	s_nop 1
	v_cndmask_b32_e32 v53, v208, v53, vcc
	v_cmp_le_i32_e32 vcc, v160, v187
	s_nop 1
	v_cndmask_b32_e32 v37, v208, v37, vcc
	v_cmp_le_i32_e32 vcc, v161, v187
	s_nop 1
	v_cndmask_b32_e32 v54, v208, v54, vcc
	v_cmp_le_i32_e32 vcc, v162, v187
	s_nop 1
	v_cndmask_b32_e32 v38, v208, v38, vcc
	v_cmp_le_i32_e32 vcc, v163, v187
	s_nop 1
	v_cndmask_b32_e32 v55, v208, v55, vcc
	v_cmp_le_i32_e32 vcc, v164, v187
	s_nop 1
	v_cndmask_b32_e32 v39, v208, v39, vcc
	v_cmp_le_i32_e32 vcc, v165, v187
	s_nop 1
	v_cndmask_b32_e32 v56, v208, v56, vcc
	v_cmp_le_i32_e32 vcc, v166, v187
	s_nop 1
	v_cndmask_b32_e32 v40, v208, v40, vcc
	v_cmp_le_i32_e32 vcc, v167, v187
	s_nop 1
	v_cndmask_b32_e32 v57, v208, v57, vcc
	v_cmp_le_i32_e32 vcc, v168, v187
	s_nop 1
	v_cndmask_b32_e32 v41, v208, v41, vcc
	v_cmp_le_i32_e32 vcc, v169, v187
	s_nop 1
	v_cndmask_b32_e32 v58, v208, v58, vcc
	v_cmp_le_i32_e32 vcc, v170, v187
	s_nop 1
	v_cndmask_b32_e32 v42, v208, v42, vcc
	v_cmp_le_i32_e32 vcc, v171, v187
	s_nop 1
	v_cndmask_b32_e32 v59, v208, v59, vcc
	v_cmp_le_i32_e32 vcc, v172, v187
	s_nop 1
	v_cndmask_b32_e32 v43, v208, v43, vcc
	v_cmp_le_i32_e32 vcc, v173, v187
	s_nop 1
	v_cndmask_b32_e32 v60, v208, v60, vcc
	v_cmp_le_i32_e32 vcc, v174, v187
	s_nop 1
	v_cndmask_b32_e32 v44, v208, v44, vcc
	v_cmp_le_i32_e32 vcc, v175, v187
	s_nop 1
	v_cndmask_b32_e32 v61, v208, v61, vcc
	v_cmp_le_i32_e32 vcc, v176, v187
	s_nop 1
	v_cndmask_b32_e32 v45, v208, v45, vcc
	v_cmp_le_i32_e32 vcc, v177, v187
	s_nop 1
	v_cndmask_b32_e32 v62, v208, v62, vcc
	v_cmp_le_i32_e32 vcc, v178, v187
	s_nop 1
	v_cndmask_b32_e32 v46, v208, v46, vcc
	v_cmp_le_i32_e32 vcc, v179, v187
	s_nop 1
	v_cndmask_b32_e32 v63, v208, v63, vcc
	v_cmp_le_i32_e32 vcc, v180, v187
	s_nop 1
	v_cndmask_b32_e32 v47, v208, v47, vcc
	v_cmp_le_i32_e32 vcc, v181, v187
	s_nop 1
	v_cndmask_b32_e32 v64, v208, v64, vcc
	v_cmp_le_i32_e32 vcc, v182, v187
	s_nop 1
	v_cndmask_b32_e32 v48, v208, v48, vcc
	v_cmp_le_i32_e32 vcc, v183, v187
	s_nop 1
	v_cndmask_b32_e32 v65, v208, v65, vcc
	v_cmp_le_i32_e32 vcc, v184, v187
	s_nop 1
	v_cndmask_b32_e32 v49, v208, v49, vcc
.Lmla_nomask:
	v_max3_f32 v244, v50, v51, v52
	v_max3_f32 v244, v244, v53, v54
	v_max3_f32 v244, v244, v55, v56
	v_max3_f32 v244, v244, v57, v58
	v_max3_f32 v244, v244, v59, v60
	v_max3_f32 v244, v244, v61, v62
	v_max3_f32 v244, v244, v63, v64
	v_max3_f32 v242, v34, v35, v36
	v_max3_f32 v242, v242, v37, v38
	v_max3_f32 v242, v242, v39, v40
	v_max3_f32 v242, v242, v41, v42
	v_max3_f32 v242, v242, v43, v44
	v_max3_f32 v242, v242, v45, v46
	v_max3_f32 v242, v242, v47, v48
	v_max3_f32 v244, v244, v65, v242
	v_max_f32_e32 v244, v244, v49
	v_cmp_lt_f32_e32 vcc, 0x41000000, v244
	s_cmp_eq_u32 s41, 0
	s_cbranch_scc1 .Lmla_rare
	s_cmp_eq_u64 vcc, 0
	s_cbranch_scc1 .Lmla_fast
; #define MFMA32(a, b, c) __builtin_amdgcn_mfma_f32_32x32x16_bf16((a), (b), (c), 0, 0, 0)
; __device__ __forceinline__ void mla_attn_phase(const Ctx&, unsigned char* ws) { const Ctx c = mk_ctx();
;     ...
;                 float mx = fmaxf(p0[0], p1[0]);
; #pragma unroll
;                 for (int i = 1; i < 16; ++i) mx = fmaxf(mx, fmaxf(p0[i], p1[i]));
;                 mx = fmaxf(mx, __shfl_xor(mx, 32));
;                 const float mnew = fmaxf(mrun, mx), alpha = __builtin_amdgcn_exp2f(mrun - mnew); const bool grow = !__all(mx <= mrun); mrun = mnew; float ls = 0.f;
; #pragma unroll
;                 for (int i = 0; i < 16; ++i) { p0[i] = __builtin_amdgcn_exp2f(p0[i] - mnew); p1[i] = __builtin_amdgcn_exp2f(p1[i] - mnew); ls += p0[i] + p1[i]; }
;                 lrun = lrun * alpha + ls;
; #pragma unroll
;                 for (int i = 0; i < 16; ++i) if (grow) { oa[0][i] *= alpha; oa[1][i] *= alpha; }
;                 bf16x8 pa[4]; pa[0] = pack8(p0, 0); pa[1] = pack8(p0, 1); pa[2] = pack8(p1, 0); pa[3] = pack8(p1, 1);
; #pragma unroll
;                 for (int db = 0; db < 2; ++db)
; #pragma unroll
;                     for (int ks = 0; ks < 4; ++ks) { const bf16* vp = Vb + (32 * db + r) * VLD + 16 * ks + 4 * hi; oa[db] = MFMA32(cat4(*(const v2u*)vp, *(const v2u*)(vp + 8)), pa[ks], oa[db]); }
.Lmla_rare:
	v_mov_b32_e32 v242, v244
	s_nop 1
	v_permlane32_swap_b32_e32 v244, v242
	s_nop 1
	v_max_f32_e32 v244, v244, v242
	s_cmp_eq_u32 s41, 0
	s_cbranch_scc1 .Lmla_rare_first
	v_max_f32_e32 v244, 0, v244
.Lmla_rare_first:
	v_add_f32_e32 v242, v189, v244
	v_and_b32_e32 v242, 0xffff0000, v242
	v_sub_f32_e32 v244, v242, v189
	v_mov_b32_e32 v189, v242
	v_sub_f32_e32 v50, v50, v244
	v_sub_f32_e32 v51, v51, v244
	v_sub_f32_e32 v52, v52, v244
	v_sub_f32_e32 v53, v53, v244
	v_sub_f32_e32 v54, v54, v244
	v_sub_f32_e32 v55, v55, v244
	v_sub_f32_e32 v56, v56, v244
	v_sub_f32_e32 v57, v57, v244
	v_sub_f32_e32 v58, v58, v244
	v_sub_f32_e32 v59, v59, v244
	v_sub_f32_e32 v60, v60, v244
	v_sub_f32_e32 v61, v61, v244
	v_sub_f32_e32 v62, v62, v244
	v_sub_f32_e32 v63, v63, v244
	v_sub_f32_e32 v64, v64, v244
	v_sub_f32_e32 v65, v65, v244
	v_sub_f32_e32 v34, v34, v244
	v_sub_f32_e32 v35, v35, v244
	v_sub_f32_e32 v36, v36, v244
	v_sub_f32_e32 v37, v37, v244
	v_sub_f32_e32 v38, v38, v244
	v_sub_f32_e32 v39, v39, v244
	v_sub_f32_e32 v40, v40, v244
	v_sub_f32_e32 v41, v41, v244
	v_sub_f32_e32 v42, v42, v244
	v_sub_f32_e32 v43, v43, v244
	v_sub_f32_e32 v44, v44, v244
	v_sub_f32_e32 v45, v45, v244
	v_sub_f32_e32 v46, v46, v244
	v_sub_f32_e32 v47, v47, v244
	v_sub_f32_e32 v48, v48, v244
	v_sub_f32_e32 v49, v49, v244
	v_cmp_gt_u32_e32 vcc, 32, v206
	v_lshrrev_b32_e32 v252, 16, v189
	v_exp_f32_e64 v244, -v244
	v_cndmask_b32_e32 v252, 0, v252, vcc
	s_cmp_eq_u32 s41, 0
	s_cbranch_scc1 .Lmla_fast
	v_pk_mul_f32 v[2:3], v[2:3], v[244:245] op_sel_hi:[1,0]
	v_pk_mul_f32 v[4:5], v[4:5], v[244:245] op_sel_hi:[1,0]
	v_pk_mul_f32 v[6:7], v[6:7], v[244:245] op_sel_hi:[1,0]
	v_pk_mul_f32 v[8:9], v[8:9], v[244:245] op_sel_hi:[1,0]
	v_pk_mul_f32 v[10:11], v[10:11], v[244:245] op_sel_hi:[1,0]
	v_pk_mul_f32 v[12:13], v[12:13], v[244:245] op_sel_hi:[1,0]
	v_pk_mul_f32 v[14:15], v[14:15], v[244:245] op_sel_hi:[1,0]
	v_pk_mul_f32 v[16:17], v[16:17], v[244:245] op_sel_hi:[1,0]
	v_pk_mul_f32 v[18:19], v[18:19], v[244:245] op_sel_hi:[1,0]
	v_pk_mul_f32 v[20:21], v[20:21], v[244:245] op_sel_hi:[1,0]
	v_pk_mul_f32 v[22:23], v[22:23], v[244:245] op_sel_hi:[1,0]
	v_pk_mul_f32 v[24:25], v[24:25], v[244:245] op_sel_hi:[1,0]
	v_pk_mul_f32 v[26:27], v[26:27], v[244:245] op_sel_hi:[1,0]
	v_pk_mul_f32 v[28:29], v[28:29], v[244:245] op_sel_hi:[1,0]
	v_pk_mul_f32 v[30:31], v[30:31], v[244:245] op_sel_hi:[1,0]
	v_pk_mul_f32 v[32:33], v[32:33], v[244:245] op_sel_hi:[1,0]
	v_mul_f32_e32 v188, v188, v244
.Lmla_fast:
	v_exp_f32_e32 v50, v50
	v_exp_f32_e32 v51, v51
	v_exp_f32_e32 v52, v52
	v_exp_f32_e32 v53, v53
	v_exp_f32_e32 v54, v54
	v_exp_f32_e32 v55, v55
	v_exp_f32_e32 v56, v56
	v_exp_f32_e32 v57, v57
	v_exp_f32_e32 v58, v58
	v_exp_f32_e32 v59, v59
	v_exp_f32_e32 v60, v60
	v_exp_f32_e32 v61, v61
	v_exp_f32_e32 v62, v62
	v_exp_f32_e32 v63, v63
	v_exp_f32_e32 v64, v64
	v_exp_f32_e32 v65, v65
	v_exp_f32_e32 v34, v34
	v_exp_f32_e32 v35, v35
	v_exp_f32_e32 v36, v36
	v_exp_f32_e32 v37, v37
	v_exp_f32_e32 v38, v38
	v_exp_f32_e32 v39, v39
	v_exp_f32_e32 v40, v40
	v_exp_f32_e32 v41, v41
	v_exp_f32_e32 v42, v42
	v_exp_f32_e32 v43, v43
	v_exp_f32_e32 v44, v44
	v_exp_f32_e32 v45, v45
	v_exp_f32_e32 v46, v46
	v_exp_f32_e32 v47, v47
	v_exp_f32_e32 v48, v48
	v_exp_f32_e32 v49, v49
	v_pk_add_f32 v[242:243], v[50:51], v[52:53]
	s_nop 0
	v_pk_add_f32 v[242:243], v[242:243], v[54:55]
	v_cvt_pk_bf16_f32 v50, v50, v51
	v_pk_add_f32 v[242:243], v[242:243], v[56:57]
	v_cvt_pk_bf16_f32 v51, v52, v53
	v_pk_add_f32 v[242:243], v[242:243], v[58:59]
	v_cvt_pk_bf16_f32 v52, v54, v55
	v_pk_add_f32 v[242:243], v[242:243], v[60:61]
	v_cvt_pk_bf16_f32 v53, v56, v57
	v_pk_add_f32 v[242:243], v[242:243], v[62:63]
	v_cvt_pk_bf16_f32 v54, v58, v59
	v_pk_add_f32 v[242:243], v[242:243], v[64:65]
	v_cvt_pk_bf16_f32 v55, v60, v61
	v_pk_add_f32 v[242:243], v[242:243], v[34:35]
	v_cvt_pk_bf16_f32 v56, v62, v63
	v_pk_add_f32 v[242:243], v[242:243], v[36:37]
	v_cvt_pk_bf16_f32 v57, v64, v65
	v_pk_add_f32 v[242:243], v[242:243], v[38:39]
	v_cvt_pk_bf16_f32 v34, v34, v35
	v_pk_add_f32 v[242:243], v[242:243], v[40:41]
	v_cvt_pk_bf16_f32 v35, v36, v37
	v_pk_add_f32 v[242:243], v[242:243], v[42:43]
	v_cvt_pk_bf16_f32 v36, v38, v39
	v_pk_add_f32 v[242:243], v[242:243], v[44:45]
	v_cvt_pk_bf16_f32 v37, v40, v41
	v_pk_add_f32 v[242:243], v[242:243], v[46:47]
	v_cvt_pk_bf16_f32 v38, v42, v43
	v_pk_add_f32 v[242:243], v[242:243], v[48:49]
	v_cvt_pk_bf16_f32 v39, v44, v45
	v_cvt_pk_bf16_f32 v40, v46, v47
	v_cvt_pk_bf16_f32 v41, v48, v49
	v_add_f32_e32 v242, v242, v243
	s_waitcnt lgkmcnt(0)
	v_add_f32_e32 v188, v188, v242
	v_mfma_f32_32x32x16_bf16 v[18:33], v[226:229], v[50:53], v[18:33]
	v_mfma_f32_32x32x16_bf16 v[2:17], v[190:193], v[50:53], v[2:17]
	v_mfma_f32_32x32x16_bf16 v[18:33], v[230:233], v[54:57], v[18:33]
	v_mfma_f32_32x32x16_bf16 v[2:17], v[214:217], v[54:57], v[2:17]
	v_mfma_f32_32x32x16_bf16 v[18:33], v[234:237], v[34:37], v[18:33]
	v_mfma_f32_32x32x16_bf16 v[2:17], v[218:221], v[34:37], v[2:17]
	v_mfma_f32_32x32x16_bf16 v[18:33], v[238:241], v[38:41], v[18:33]
	v_mfma_f32_32x32x16_bf16 v[2:17], v[222:225], v[38:41], v[2:17]
